# grid barrier: waiters poll less often (s_sleep 6 between polls)
# speedup vs baseline: 1.0041x; 1.0041x over previous
.Lxb0_wait:
	global_load_dword v248, v253, s[60:61] sc1
	v_add_u32_e32 v252, 1, v252
	s_waitcnt vmcnt(0)
	v_cmp_ge_u32_e32 vcc, v248, v249
	s_cbranch_vccnz .Lxb0_wdone
	v_cmp_gt_u32_e32 vcc, 0x100000, v252
	s_cbranch_vccz .Lxb0_wdone
	s_sleep 6
	s_branch .Lxb0_wait
